# stick-breaking early-exit test: both flag LDS reads issued before one wait
# speedup vs baseline: 1.0023x; 1.0023x over previous
; __device__ __forceinline__ void attn_b_unit(LAS unsigned char* lds, bf16_t* QKV, int unit) {
;     ...
;         for (int of = 8; of >= 1; of >>= 1) am = fmaxf(am, __shfl_xor(am, of));
;         if (lane == 0) flags[wid] = am;
;         __syncthreads();
;         float fm = flags[0];
; #pragma unroll
;         for (int i = 1; i < 8; ++i) fm = fmaxf(fm, flags[i]);
;         if (fm < -110.0f * LOG2E) break;
.LBB0_193:
	s_or_b64 exec, exec, s[0:1]
	v_readlane_b32 s0, v254, 54
	s_waitcnt lgkmcnt(0)
	s_barrier
	v_mov_b32_e32 v80, s0
	v_readlane_b32 s0, v254, 55
	ds_read_b128 v[80:83], v80
	s_cmp_lg_u32 s33, 0
	s_nop 1
	v_mov_b32_e32 v85, s0
	ds_read_b128 v[88:91], v85
	s_mov_b32 s0, 0xc31eb24b
	s_waitcnt lgkmcnt(0)
	v_max_f32_e32 v81, v81, v81
	v_max_f32_e32 v80, v80, v80
	v_max_f32_e32 v80, v80, v81
	v_max3_f32 v84, v80, v82, v83
	v_max3_f32 v80, v84, v88, v89
	v_max3_f32 v80, v80, v90, v91
	v_cmp_ngt_f32_e32 vcc, s0, v80
	s_cselect_b64 s[0:1], -1, 0
	s_and_b64 s[0:1], vcc, s[0:1]
	s_and_b64 vcc, exec, s[0:1]
	s_cbranch_vccz .LBB0_191
